# GU epilogue through LDS: bf16 tile image in idle b=1 buffers, whole-row dwordx4 stores (quarter-wave coalesced)
# baseline (speedup 1.0000x reference)
.LBB0_734:
	v_and_b32_e32 v240, 63, v131
	v_lshrrev_b32_e32 v241, 6, v131
	v_and_b32_e32 v242, 15, v240
	v_lshrrev_b32_e32 v243, 4, v240
	v_lshrrev_b32_e32 v244, 2, v241
	v_and_b32_e32 v245, 3, v241
	v_lshl_add_u32 v244, v244, 6, v242
	v_lshlrev_b32_e32 v244, 8, v244
	v_lshrrev_b32_e32 v246, 1, v243
	v_lshl_add_u32 v245, v245, 1, v246
	v_xor_b32_e32 v245, v245, v242
	v_lshl_add_u32 v244, v245, 4, v244
	v_and_b32_e32 v246, 1, v243
	v_lshl_add_u32 v244, v246, 3, v244
	v_xor_b32_e32 v245, 0x80, v244
	v_add_u32_e32 v246, 0x8020, v244
	v_add_u32_e32 v247, 0x8020, v245
	v_add_u32_e32 v248, 0x18020, v244
	v_add_u32_e32 v249, 0x18020, v245
	v_lshl_add_u32 v240, v241, 5, v243
	v_add_u32_e32 v240, s29, v240
	v_lshlrev_b32_e32 v241, 4, v242
	v_add_u32_e32 v241, s28, v241
	v_mul_f32_e32 v156, 0xbfb8aa3b, v124
	v_mul_f32_e32 v157, 0xbfb8aa3b, v125
	v_exp_f32_e32 v156, v156
	v_exp_f32_e32 v157, v157
	v_add_u32_e32 v158, s28, v150
	v_ashrrev_i32_e32 v154, 1, v158
	v_add_f32_e32 v156, 1.0, v156
	v_add_f32_e32 v157, 1.0, v157
	v_rcp_f32_e32 v156, v156
	v_rcp_f32_e32 v157, v157
	v_add_u32_e32 v153, s29, v133
	v_ashrrev_i32_e32 v155, 31, v154
	s_movk_i32 s15, 0x1600
	v_pk_mul_f32 v[124:125], v[124:125], v[156:157]
	v_mad_i64_i32 v[148:149], s[28:29], v153, s15, v[136:137]
	v_pk_mul_f32 v[120:121], v[120:121], v[124:125]
	v_mul_f32_e32 v124, 0xbfb8aa3b, v126
	v_mul_f32_e32 v125, 0xbfb8aa3b, v127
	v_exp_f32_e32 v124, v124
	v_exp_f32_e32 v125, v125
	v_add_u32_e32 v142, 16, v153
	v_mad_i64_i32 v[146:147], s[28:29], v142, s15, v[136:137]
	v_add_f32_e32 v124, 1.0, v124
	v_add_f32_e32 v125, 1.0, v125
	v_rcp_f32_e32 v124, v124
	v_rcp_f32_e32 v125, v125
	v_add_u32_e32 v142, 32, v153
	v_mad_i64_i32 v[144:145], s[28:29], v142, s15, v[136:137]
	v_pk_mul_f32 v[124:125], v[126:127], v[124:125]
	v_add_u32_e32 v142, 48, v153
	v_pk_mul_f32 v[122:123], v[122:123], v[124:125]
	v_cvt_pk_bf16_f32 v208, v120, v121
	v_lshlrev_b64 v[120:121], 1, v[154:155]
	v_cvt_pk_bf16_f32 v209, v122, v123
	v_mul_f32_e32 v122, 0xbfb8aa3b, v116
	v_mul_f32_e32 v123, 0xbfb8aa3b, v117
	v_exp_f32_e32 v122, v122
	v_exp_f32_e32 v123, v123
	v_mad_i64_i32 v[142:143], s[28:29], v142, s15, v[136:137]
	v_add_f32_e32 v122, 1.0, v122
	v_add_f32_e32 v123, 1.0, v123
	v_rcp_f32_e32 v122, v122
	v_rcp_f32_e32 v123, v123
	s_andn2_b64 vcc, exec, s[12:13]
	v_pk_mul_f32 v[116:117], v[116:117], v[122:123]
	s_nop 0
	v_pk_mul_f32 v[112:113], v[112:113], v[116:117]
	v_mul_f32_e32 v116, 0xbfb8aa3b, v118
	v_mul_f32_e32 v117, 0xbfb8aa3b, v119
	v_exp_f32_e32 v116, v116
	v_exp_f32_e32 v117, v117
	v_cvt_pk_bf16_f32 v210, v112, v113
	v_add_f32_e32 v116, 1.0, v116
	v_add_f32_e32 v117, 1.0, v117
	v_rcp_f32_e32 v116, v116
	v_rcp_f32_e32 v117, v117
	s_nop 0
	v_pk_mul_f32 v[116:117], v[118:119], v[116:117]
	s_nop 0
	v_pk_mul_f32 v[114:115], v[114:115], v[116:117]
	s_nop 0
	v_cvt_pk_bf16_f32 v211, v114, v115
	ds_write_b64 v246, v[208:209]
	ds_write_b64 v246, v[210:211] offset:4096
	v_mul_f32_e32 v112, 0xbfb8aa3b, v108
	v_mul_f32_e32 v113, 0xbfb8aa3b, v109
	v_exp_f32_e32 v112, v112
	v_exp_f32_e32 v113, v113
	v_add_f32_e32 v112, 1.0, v112
	v_add_f32_e32 v113, 1.0, v113
	v_rcp_f32_e32 v112, v112
	v_rcp_f32_e32 v113, v113
	s_nop 0
	v_pk_mul_f32 v[108:109], v[108:109], v[112:113]
	s_nop 0
	v_pk_mul_f32 v[104:105], v[104:105], v[108:109]
	v_mul_f32_e32 v108, 0xbfb8aa3b, v110
	v_mul_f32_e32 v109, 0xbfb8aa3b, v111
	v_exp_f32_e32 v108, v108
	v_exp_f32_e32 v109, v109
	v_cvt_pk_bf16_f32 v212, v104, v105
	v_add_f32_e32 v108, 1.0, v108
	v_add_f32_e32 v109, 1.0, v109
	v_rcp_f32_e32 v108, v108
	v_rcp_f32_e32 v109, v109
	s_nop 0
	v_pk_mul_f32 v[108:109], v[110:111], v[108:109]
	s_nop 0
	v_pk_mul_f32 v[106:107], v[106:107], v[108:109]
	s_nop 0
	v_cvt_pk_bf16_f32 v213, v106, v107
	v_mul_f32_e32 v104, 0xbfb8aa3b, v100
	v_mul_f32_e32 v105, 0xbfb8aa3b, v101
	v_exp_f32_e32 v104, v104
	v_exp_f32_e32 v105, v105
	v_add_f32_e32 v104, 1.0, v104
	v_add_f32_e32 v105, 1.0, v105
	v_rcp_f32_e32 v104, v104
	v_rcp_f32_e32 v105, v105
	s_nop 0
	v_pk_mul_f32 v[100:101], v[100:101], v[104:105]
	s_nop 0
	v_pk_mul_f32 v[96:97], v[96:97], v[100:101]
	v_mul_f32_e32 v100, 0xbfb8aa3b, v102
	v_mul_f32_e32 v101, 0xbfb8aa3b, v103
	v_exp_f32_e32 v100, v100
	v_exp_f32_e32 v101, v101
	v_cvt_pk_bf16_f32 v214, v96, v97
	v_add_f32_e32 v100, 1.0, v100
	v_add_f32_e32 v101, 1.0, v101
	v_rcp_f32_e32 v100, v100
	v_rcp_f32_e32 v101, v101
	s_nop 0
	v_pk_mul_f32 v[100:101], v[102:103], v[100:101]
	s_nop 0
	v_pk_mul_f32 v[98:99], v[98:99], v[100:101]
	s_nop 0
	v_cvt_pk_bf16_f32 v215, v98, v99
	ds_write_b64 v246, v[212:213] offset:8192
	ds_write_b64 v246, v[214:215] offset:12288
	v_mul_f32_e32 v98, 0xbfb8aa3b, v92
	v_mul_f32_e32 v99, 0xbfb8aa3b, v93
	v_exp_f32_e32 v98, v98
	v_exp_f32_e32 v99, v99
	v_add_u32_e32 v96, 0x80, v158
	v_ashrrev_i32_e32 v96, 1, v96
	v_add_f32_e32 v98, 1.0, v98
	v_add_f32_e32 v99, 1.0, v99
	v_rcp_f32_e32 v98, v98
	v_rcp_f32_e32 v99, v99
	v_ashrrev_i32_e32 v97, 31, v96
	v_pk_mul_f32 v[92:93], v[92:93], v[98:99]
	s_nop 0
	v_pk_mul_f32 v[88:89], v[88:89], v[92:93]
	v_mul_f32_e32 v92, 0xbfb8aa3b, v94
	v_mul_f32_e32 v93, 0xbfb8aa3b, v95
	v_exp_f32_e32 v92, v92
	v_exp_f32_e32 v93, v93
	v_add_f32_e32 v92, 1.0, v92
	v_add_f32_e32 v93, 1.0, v93
	v_rcp_f32_e32 v92, v92
	v_rcp_f32_e32 v93, v93
	s_nop 0
	v_pk_mul_f32 v[92:93], v[94:95], v[92:93]
	s_nop 0
	v_pk_mul_f32 v[90:91], v[90:91], v[92:93]
	v_cvt_pk_bf16_f32 v216, v88, v89
	v_lshlrev_b64 v[88:89], 1, v[96:97]
	v_cvt_pk_bf16_f32 v217, v90, v91
	v_mul_f32_e32 v90, 0xbfb8aa3b, v84
	v_mul_f32_e32 v91, 0xbfb8aa3b, v85
	v_exp_f32_e32 v90, v90
	v_exp_f32_e32 v91, v91
	v_add_f32_e32 v90, 1.0, v90
	v_add_f32_e32 v91, 1.0, v91
	v_rcp_f32_e32 v90, v90
	v_rcp_f32_e32 v91, v91
	s_nop 0
	v_pk_mul_f32 v[84:85], v[84:85], v[90:91]
	s_nop 0
	v_pk_mul_f32 v[80:81], v[80:81], v[84:85]
	v_mul_f32_e32 v84, 0xbfb8aa3b, v86
	v_mul_f32_e32 v85, 0xbfb8aa3b, v87
	v_exp_f32_e32 v84, v84
	v_exp_f32_e32 v85, v85
	v_cvt_pk_bf16_f32 v218, v80, v81
	v_add_f32_e32 v84, 1.0, v84
	v_add_f32_e32 v85, 1.0, v85
	v_rcp_f32_e32 v84, v84
	v_rcp_f32_e32 v85, v85
	s_nop 0
	v_pk_mul_f32 v[84:85], v[86:87], v[84:85]
	s_nop 0
	v_pk_mul_f32 v[82:83], v[82:83], v[84:85]
	s_nop 0
	v_cvt_pk_bf16_f32 v219, v82, v83
	ds_write_b64 v247, v[216:217]
	ds_write_b64 v247, v[218:219] offset:4096
	v_mul_f32_e32 v80, 0xbfb8aa3b, v76
	v_mul_f32_e32 v81, 0xbfb8aa3b, v77
	v_exp_f32_e32 v80, v80
	v_exp_f32_e32 v81, v81
	v_add_f32_e32 v80, 1.0, v80
	v_add_f32_e32 v81, 1.0, v81
	v_rcp_f32_e32 v80, v80
	v_rcp_f32_e32 v81, v81
	s_nop 0
	v_pk_mul_f32 v[76:77], v[76:77], v[80:81]
	s_nop 0
	v_pk_mul_f32 v[72:73], v[72:73], v[76:77]
	v_mul_f32_e32 v76, 0xbfb8aa3b, v78
	v_mul_f32_e32 v77, 0xbfb8aa3b, v79
	v_exp_f32_e32 v76, v76
	v_exp_f32_e32 v77, v77
	v_cvt_pk_bf16_f32 v220, v72, v73
	v_add_f32_e32 v76, 1.0, v76
	v_add_f32_e32 v77, 1.0, v77
	v_rcp_f32_e32 v76, v76
	v_rcp_f32_e32 v77, v77
	s_nop 0
	v_pk_mul_f32 v[76:77], v[78:79], v[76:77]
	s_nop 0
	v_pk_mul_f32 v[74:75], v[74:75], v[76:77]
	s_nop 0
	v_cvt_pk_bf16_f32 v221, v74, v75
	v_mul_f32_e32 v72, 0xbfb8aa3b, v68
	v_mul_f32_e32 v73, 0xbfb8aa3b, v69
	v_exp_f32_e32 v72, v72
	v_exp_f32_e32 v73, v73
	v_add_f32_e32 v72, 1.0, v72
	v_add_f32_e32 v73, 1.0, v73
	v_rcp_f32_e32 v72, v72
	v_rcp_f32_e32 v73, v73
	s_nop 0
	v_pk_mul_f32 v[68:69], v[68:69], v[72:73]
	v_mul_f32_e32 v72, 0xbfb8aa3b, v60
	v_mul_f32_e32 v73, 0xbfb8aa3b, v61
	v_exp_f32_e32 v72, v72
	v_exp_f32_e32 v73, v73
	v_pk_mul_f32 v[64:65], v[64:65], v[68:69]
	v_mul_f32_e32 v68, 0xbfb8aa3b, v70
	v_add_f32_e32 v72, 1.0, v72
	v_add_f32_e32 v73, 1.0, v73
	v_rcp_f32_e32 v72, v72
	v_rcp_f32_e32 v73, v73
	v_mul_f32_e32 v69, 0xbfb8aa3b, v71
	v_exp_f32_e32 v68, v68
	v_exp_f32_e32 v69, v69
	v_pk_mul_f32 v[60:61], v[60:61], v[72:73]
	v_cvt_pk_bf16_f32 v222, v64, v65
	v_pk_mul_f32 v[56:57], v[56:57], v[60:61]
	v_mul_f32_e32 v60, 0xbfb8aa3b, v62
	v_mul_f32_e32 v61, 0xbfb8aa3b, v63
	v_exp_f32_e32 v60, v60
	v_exp_f32_e32 v61, v61
	v_add_f32_e32 v68, 1.0, v68
	v_add_f32_e32 v69, 1.0, v69
	v_rcp_f32_e32 v68, v68
	v_rcp_f32_e32 v69, v69
	v_add_f32_e32 v60, 1.0, v60
	v_add_f32_e32 v61, 1.0, v61
	v_rcp_f32_e32 v60, v60
	v_rcp_f32_e32 v61, v61
	v_pk_mul_f32 v[68:69], v[70:71], v[68:69]
	v_cvt_pk_bf16_f32 v224, v56, v57
	v_pk_mul_f32 v[66:67], v[66:67], v[68:69]
	v_pk_mul_f32 v[60:61], v[62:63], v[60:61]
	v_cvt_pk_bf16_f32 v223, v66, v67
	ds_write_b64 v247, v[220:221] offset:8192
	ds_write_b64 v247, v[222:223] offset:12288
	v_add_u32_e32 v64, 0x80, v153
	v_mad_i64_i32 v[70:71], s[28:29], v64, s15, v[136:137]
	v_pk_mul_f32 v[58:59], v[58:59], v[60:61]
	v_add_u32_e32 v64, 0x90, v153
	v_cvt_pk_bf16_f32 v225, v58, v59
	v_mul_f32_e32 v56, 0xbfb8aa3b, v52
	v_mul_f32_e32 v57, 0xbfb8aa3b, v53
	v_exp_f32_e32 v56, v56
	v_exp_f32_e32 v57, v57
	v_mad_i64_i32 v[68:69], s[28:29], v64, s15, v[136:137]
	v_add_f32_e32 v56, 1.0, v56
	v_add_f32_e32 v57, 1.0, v57
	v_rcp_f32_e32 v56, v56
	v_rcp_f32_e32 v57, v57
	v_add_u32_e32 v64, 0xa0, v153
	v_mad_i64_i32 v[66:67], s[28:29], v64, s15, v[136:137]
	v_pk_mul_f32 v[52:53], v[52:53], v[56:57]
	v_add_u32_e32 v64, 0xb0, v153
	v_pk_mul_f32 v[48:49], v[48:49], v[52:53]
	v_mul_f32_e32 v52, 0xbfb8aa3b, v54
	v_mul_f32_e32 v53, 0xbfb8aa3b, v55
	v_exp_f32_e32 v52, v52
	v_exp_f32_e32 v53, v53
	v_cvt_pk_bf16_f32 v226, v48, v49
	v_mad_i64_i32 v[64:65], s[28:29], v64, s15, v[136:137]
	v_add_f32_e32 v52, 1.0, v52
	v_add_f32_e32 v53, 1.0, v53
	v_rcp_f32_e32 v52, v52
	v_rcp_f32_e32 v53, v53
	s_mov_b32 s28, s16
	s_mov_b32 s29, s14
	v_pk_mul_f32 v[52:53], v[54:55], v[52:53]
	s_nop 0
	v_pk_mul_f32 v[50:51], v[50:51], v[52:53]
	s_nop 0
	v_cvt_pk_bf16_f32 v227, v50, v51
	ds_write_b64 v248, v[224:225]
	ds_write_b64 v248, v[226:227] offset:4096
	v_mul_f32_e32 v48, 0xbfb8aa3b, v44
	v_mul_f32_e32 v49, 0xbfb8aa3b, v45
	v_exp_f32_e32 v48, v48
	v_exp_f32_e32 v49, v49
	v_add_f32_e32 v48, 1.0, v48
	v_add_f32_e32 v49, 1.0, v49
	v_rcp_f32_e32 v48, v48
	v_rcp_f32_e32 v49, v49
	s_nop 0
	v_pk_mul_f32 v[44:45], v[44:45], v[48:49]
	s_nop 0
	v_pk_mul_f32 v[40:41], v[40:41], v[44:45]
	v_mul_f32_e32 v44, 0xbfb8aa3b, v46
	v_mul_f32_e32 v45, 0xbfb8aa3b, v47
	v_exp_f32_e32 v44, v44
	v_exp_f32_e32 v45, v45
	v_cvt_pk_bf16_f32 v228, v40, v41
	v_add_f32_e32 v44, 1.0, v44
	v_add_f32_e32 v45, 1.0, v45
	v_rcp_f32_e32 v44, v44
	v_rcp_f32_e32 v45, v45
	s_nop 0
	v_pk_mul_f32 v[44:45], v[46:47], v[44:45]
	s_nop 0
	v_pk_mul_f32 v[42:43], v[42:43], v[44:45]
	s_nop 0
	v_cvt_pk_bf16_f32 v229, v42, v43
	v_mul_f32_e32 v40, 0xbfb8aa3b, v36
	v_mul_f32_e32 v41, 0xbfb8aa3b, v37
	v_exp_f32_e32 v40, v40
	v_exp_f32_e32 v41, v41
	v_add_f32_e32 v40, 1.0, v40
	v_add_f32_e32 v41, 1.0, v41
	v_rcp_f32_e32 v40, v40
	v_rcp_f32_e32 v41, v41
	s_nop 0
	v_pk_mul_f32 v[36:37], v[36:37], v[40:41]
	s_nop 0
	v_pk_mul_f32 v[32:33], v[32:33], v[36:37]
	v_mul_f32_e32 v36, 0xbfb8aa3b, v38
	v_mul_f32_e32 v37, 0xbfb8aa3b, v39
	v_exp_f32_e32 v36, v36
	v_exp_f32_e32 v37, v37
	v_cvt_pk_bf16_f32 v230, v32, v33
	v_add_f32_e32 v36, 1.0, v36
	v_add_f32_e32 v37, 1.0, v37
	v_rcp_f32_e32 v36, v36
	v_rcp_f32_e32 v37, v37
	s_nop 0
	v_pk_mul_f32 v[36:37], v[38:39], v[36:37]
	s_nop 0
	v_pk_mul_f32 v[34:35], v[34:35], v[36:37]
	s_nop 0
	v_cvt_pk_bf16_f32 v231, v34, v35
	ds_write_b64 v248, v[228:229] offset:8192
	ds_write_b64 v248, v[230:231] offset:12288
	v_mul_f32_e32 v32, 0xbfb8aa3b, v28
	v_mul_f32_e32 v33, 0xbfb8aa3b, v29
	v_exp_f32_e32 v32, v32
	v_exp_f32_e32 v33, v33
	v_add_f32_e32 v32, 1.0, v32
	v_add_f32_e32 v33, 1.0, v33
	v_rcp_f32_e32 v32, v32
	v_rcp_f32_e32 v33, v33
	s_nop 0
	v_pk_mul_f32 v[28:29], v[28:29], v[32:33]
	s_nop 0
	v_pk_mul_f32 v[24:25], v[24:25], v[28:29]
	v_mul_f32_e32 v28, 0xbfb8aa3b, v30
	v_mul_f32_e32 v29, 0xbfb8aa3b, v31
	v_exp_f32_e32 v28, v28
	v_exp_f32_e32 v29, v29
	v_cvt_pk_bf16_f32 v232, v24, v25
	v_add_f32_e32 v28, 1.0, v28
	v_add_f32_e32 v29, 1.0, v29
	v_rcp_f32_e32 v28, v28
	v_rcp_f32_e32 v29, v29
	s_nop 0
	v_pk_mul_f32 v[28:29], v[30:31], v[28:29]
	s_nop 0
	v_pk_mul_f32 v[26:27], v[26:27], v[28:29]
	s_nop 0
	v_cvt_pk_bf16_f32 v233, v26, v27
	v_mul_f32_e32 v24, 0xbfb8aa3b, v20
	v_mul_f32_e32 v25, 0xbfb8aa3b, v21
	v_exp_f32_e32 v24, v24
	v_exp_f32_e32 v25, v25
	v_add_f32_e32 v24, 1.0, v24
	v_add_f32_e32 v25, 1.0, v25
	v_rcp_f32_e32 v24, v24
	v_rcp_f32_e32 v25, v25
	s_nop 0
	v_pk_mul_f32 v[20:21], v[20:21], v[24:25]
	s_nop 0
	v_pk_mul_f32 v[16:17], v[16:17], v[20:21]
	v_mul_f32_e32 v20, 0xbfb8aa3b, v22
	v_mul_f32_e32 v21, 0xbfb8aa3b, v23
	v_exp_f32_e32 v20, v20
	v_exp_f32_e32 v21, v21
	v_cvt_pk_bf16_f32 v234, v16, v17
	v_add_f32_e32 v20, 1.0, v20
	v_add_f32_e32 v21, 1.0, v21
	v_rcp_f32_e32 v20, v20
	v_rcp_f32_e32 v21, v21
	s_nop 0
	v_pk_mul_f32 v[20:21], v[22:23], v[20:21]
	s_nop 0
	v_pk_mul_f32 v[18:19], v[18:19], v[20:21]
	s_nop 0
	v_cvt_pk_bf16_f32 v235, v18, v19
	ds_write_b64 v249, v[232:233]
	ds_write_b64 v249, v[234:235] offset:4096
	v_mul_f32_e32 v16, 0xbfb8aa3b, v12
	v_mul_f32_e32 v17, 0xbfb8aa3b, v13
	v_exp_f32_e32 v16, v16
	v_exp_f32_e32 v17, v17
	v_add_f32_e32 v16, 1.0, v16
	v_add_f32_e32 v17, 1.0, v17
	v_rcp_f32_e32 v16, v16
	v_rcp_f32_e32 v17, v17
	s_nop 0
	v_pk_mul_f32 v[12:13], v[12:13], v[16:17]
	s_nop 0
	v_pk_mul_f32 v[8:9], v[8:9], v[12:13]
	v_mul_f32_e32 v12, 0xbfb8aa3b, v14
	v_mul_f32_e32 v13, 0xbfb8aa3b, v15
	v_exp_f32_e32 v12, v12
	v_exp_f32_e32 v13, v13
	v_cvt_pk_bf16_f32 v236, v8, v9
	v_add_f32_e32 v12, 1.0, v12
	v_add_f32_e32 v13, 1.0, v13
	v_rcp_f32_e32 v12, v12
	v_rcp_f32_e32 v13, v13
	s_nop 0
	v_pk_mul_f32 v[12:13], v[14:15], v[12:13]
	s_nop 0
	v_pk_mul_f32 v[10:11], v[10:11], v[12:13]
	s_nop 0
	v_cvt_pk_bf16_f32 v237, v10, v11
	v_mul_f32_e32 v8, 0xbfb8aa3b, v4
	v_mul_f32_e32 v9, 0xbfb8aa3b, v5
	v_exp_f32_e32 v8, v8
	v_exp_f32_e32 v9, v9
	v_add_f32_e32 v8, 1.0, v8
	v_add_f32_e32 v9, 1.0, v9
	v_rcp_f32_e32 v8, v8
	v_rcp_f32_e32 v9, v9
	s_nop 0
	v_pk_mul_f32 v[4:5], v[4:5], v[8:9]
	s_nop 0
	v_pk_mul_f32 v[0:1], v[0:1], v[4:5]
	v_mul_f32_e32 v4, 0xbfb8aa3b, v6
	v_mul_f32_e32 v5, 0xbfb8aa3b, v7
	v_exp_f32_e32 v4, v4
	v_exp_f32_e32 v5, v5
	v_cvt_pk_bf16_f32 v238, v0, v1
	v_add_f32_e32 v4, 1.0, v4
	v_add_f32_e32 v5, 1.0, v5
	v_rcp_f32_e32 v4, v4
	v_rcp_f32_e32 v5, v5
	s_nop 0
	v_pk_mul_f32 v[4:5], v[6:7], v[4:5]
	s_nop 0
	v_pk_mul_f32 v[2:3], v[2:3], v[4:5]
	s_nop 0
	v_cvt_pk_bf16_f32 v239, v2, v3
	ds_write_b64 v249, v[236:237] offset:8192
	ds_write_b64 v249, v[238:239] offset:12288
	s_waitcnt lgkmcnt(0)
	s_barrier
	v_and_b32_e32 v58, 63, v131
	v_lshrrev_b32_e32 v59, 6, v131
	v_and_b32_e32 v60, 15, v58
	v_lshrrev_b32_e32 v61, 4, v58
	v_and_b32_e32 v62, 3, v59
	v_lshl_add_u32 v62, v62, 5, v61
	v_lshlrev_b32_e32 v62, 8, v62
	v_lshrrev_b32_e32 v63, 2, v59
	v_lshl_add_u32 v62, v63, 16, v62
	v_add_u32_e32 v62, 0x8020, v62
	v_xor_b32_e32 v63, v60, v61
	v_lshl_add_u32 v98, v63, 4, v62
	v_xor_b32_e32 v64, 4, v63
	v_lshl_add_u32 v99, v64, 4, v62
	v_xor_b32_e32 v64, 8, v63
	v_lshl_add_u32 v100, v64, 4, v62
	v_xor_b32_e32 v64, 12, v63
	v_lshl_add_u32 v101, v64, 4, v62
	ds_read_b128 v[4:7], v98
	ds_read_b128 v[8:11], v99 offset:1024
	ds_read_b128 v[20:23], v100 offset:2048
	ds_read_b128 v[24:27], v101 offset:3072
	ds_read_b128 v[28:31], v98 offset:4096
	ds_read_b128 v[32:35], v99 offset:5120
	ds_read_b128 v[36:39], v100 offset:6144
	ds_read_b128 v[40:43], v101 offset:7168
	v_mov_b32_e32 v102, 0x1600
	v_mov_b32_e32 v50, s80
	v_mov_b32_e32 v51, s81
	v_mad_i64_i32 v[46:47], s[94:95], v240, v102, v[50:51]
	v_mov_b32_e32 v44, v241
	v_mov_b32_e32 v45, 0
	v_mov_b32_e32 v48, 0x5800
	v_mov_b32_e32 v49, 0
	v_lshl_add_u64 v[46:47], v[46:47], 0, v[44:45]
	s_waitcnt lgkmcnt(7)
	global_store_dwordx4 v[46:47], v[4:7], off
	v_lshl_add_u64 v[46:47], v[46:47], 0, v[48:49]
	s_waitcnt lgkmcnt(6)
	global_store_dwordx4 v[46:47], v[8:11], off
	v_lshl_add_u64 v[46:47], v[46:47], 0, v[48:49]
	s_waitcnt lgkmcnt(5)
	global_store_dwordx4 v[46:47], v[20:23], off
	v_lshl_add_u64 v[46:47], v[46:47], 0, v[48:49]
	s_waitcnt lgkmcnt(4)
	global_store_dwordx4 v[46:47], v[24:27], off
	v_lshl_add_u64 v[46:47], v[46:47], 0, v[48:49]
	s_waitcnt lgkmcnt(3)
	global_store_dwordx4 v[46:47], v[28:31], off
	v_lshl_add_u64 v[46:47], v[46:47], 0, v[48:49]
	s_waitcnt lgkmcnt(2)
	global_store_dwordx4 v[46:47], v[32:35], off
	v_lshl_add_u64 v[46:47], v[46:47], 0, v[48:49]
	s_waitcnt lgkmcnt(1)
	global_store_dwordx4 v[46:47], v[36:39], off
	v_lshl_add_u64 v[46:47], v[46:47], 0, v[48:49]
	s_waitcnt lgkmcnt(0)
	global_store_dwordx4 v[46:47], v[40:43], off
	s_cbranch_vccz .LBB0_743

.LBB0_1961:
	v_and_b32_e32 v240, 63, v131
	v_lshrrev_b32_e32 v241, 6, v131
	v_and_b32_e32 v242, 15, v240
	v_lshrrev_b32_e32 v243, 4, v240
	v_lshrrev_b32_e32 v244, 2, v241
	v_and_b32_e32 v245, 3, v241
	v_lshl_add_u32 v244, v244, 6, v242
	v_lshlrev_b32_e32 v244, 8, v244
	v_lshrrev_b32_e32 v246, 1, v243
	v_lshl_add_u32 v245, v245, 1, v246
	v_xor_b32_e32 v245, v245, v242
	v_lshl_add_u32 v244, v245, 4, v244
	v_and_b32_e32 v246, 1, v243
	v_lshl_add_u32 v244, v246, 3, v244
	v_xor_b32_e32 v245, 0x80, v244
	v_add_u32_e32 v246, 0x8020, v244
	v_add_u32_e32 v247, 0x8020, v245
	v_add_u32_e32 v248, 0x18020, v244
	v_add_u32_e32 v249, 0x18020, v245
	v_lshl_add_u32 v240, v241, 5, v243
	v_add_u32_e32 v240, s16, v240
	v_lshlrev_b32_e32 v241, 4, v242
	v_add_u32_e32 v241, s18, v241
	v_mul_f32_e32 v156, 0xbfb8aa3b, v124
	v_mul_f32_e32 v157, 0xbfb8aa3b, v125
	v_exp_f32_e32 v156, v156
	v_exp_f32_e32 v157, v157
	v_add_u32_e32 v158, s18, v150
	v_ashrrev_i32_e32 v154, 1, v158
	v_add_f32_e32 v156, 1.0, v156
	v_add_f32_e32 v157, 1.0, v157
	v_rcp_f32_e32 v156, v156
	v_rcp_f32_e32 v157, v157
	v_add_u32_e32 v153, s16, v133
	v_ashrrev_i32_e32 v155, 31, v154
	s_movk_i32 s13, 0x1600
	v_pk_mul_f32 v[124:125], v[124:125], v[156:157]
	v_mad_i64_i32 v[148:149], s[34:35], v153, s13, v[136:137]
	v_pk_mul_f32 v[120:121], v[120:121], v[124:125]
	v_mul_f32_e32 v124, 0xbfb8aa3b, v126
	v_mul_f32_e32 v125, 0xbfb8aa3b, v127
	v_exp_f32_e32 v124, v124
	v_exp_f32_e32 v125, v125
	v_add_u32_e32 v142, 16, v153
	v_mad_i64_i32 v[146:147], s[34:35], v142, s13, v[136:137]
	v_add_f32_e32 v124, 1.0, v124
	v_add_f32_e32 v125, 1.0, v125
	v_rcp_f32_e32 v124, v124
	v_rcp_f32_e32 v125, v125
	v_add_u32_e32 v142, 32, v153
	v_mad_i64_i32 v[144:145], s[34:35], v142, s13, v[136:137]
	v_pk_mul_f32 v[124:125], v[126:127], v[124:125]
	v_add_u32_e32 v142, 48, v153
	v_pk_mul_f32 v[122:123], v[122:123], v[124:125]
	v_cvt_pk_bf16_f32 v208, v120, v121
	v_lshlrev_b64 v[120:121], 1, v[154:155]
	v_cvt_pk_bf16_f32 v209, v122, v123
	v_mul_f32_e32 v122, 0xbfb8aa3b, v116
	v_mul_f32_e32 v123, 0xbfb8aa3b, v117
	v_exp_f32_e32 v122, v122
	v_exp_f32_e32 v123, v123
	v_mad_i64_i32 v[142:143], s[34:35], v142, s13, v[136:137]
	v_add_f32_e32 v122, 1.0, v122
	v_add_f32_e32 v123, 1.0, v123
	v_rcp_f32_e32 v122, v122
	v_rcp_f32_e32 v123, v123
	s_andn2_b64 vcc, exec, s[10:11]
	s_mov_b32 s18, s14
	s_mov_b32 s16, s12
	v_pk_mul_f32 v[116:117], v[116:117], v[122:123]
	s_nop 0
	v_pk_mul_f32 v[112:113], v[112:113], v[116:117]
	v_mul_f32_e32 v116, 0xbfb8aa3b, v118
	v_mul_f32_e32 v117, 0xbfb8aa3b, v119
	v_exp_f32_e32 v116, v116
	v_exp_f32_e32 v117, v117
	v_cvt_pk_bf16_f32 v210, v112, v113
	v_add_f32_e32 v116, 1.0, v116
	v_add_f32_e32 v117, 1.0, v117
	v_rcp_f32_e32 v116, v116
	v_rcp_f32_e32 v117, v117
	s_nop 0
	v_pk_mul_f32 v[116:117], v[118:119], v[116:117]
	s_nop 0
	v_pk_mul_f32 v[114:115], v[114:115], v[116:117]
	s_nop 0
	v_cvt_pk_bf16_f32 v211, v114, v115
	ds_write_b64 v246, v[208:209]
	ds_write_b64 v246, v[210:211] offset:4096
	v_mul_f32_e32 v112, 0xbfb8aa3b, v108
	v_mul_f32_e32 v113, 0xbfb8aa3b, v109
	v_exp_f32_e32 v112, v112
	v_exp_f32_e32 v113, v113
	v_add_f32_e32 v112, 1.0, v112
	v_add_f32_e32 v113, 1.0, v113
	v_rcp_f32_e32 v112, v112
	v_rcp_f32_e32 v113, v113
	s_nop 0
	v_pk_mul_f32 v[108:109], v[108:109], v[112:113]
	s_nop 0
	v_pk_mul_f32 v[104:105], v[104:105], v[108:109]
	v_mul_f32_e32 v108, 0xbfb8aa3b, v110
	v_mul_f32_e32 v109, 0xbfb8aa3b, v111
	v_exp_f32_e32 v108, v108
	v_exp_f32_e32 v109, v109
	v_cvt_pk_bf16_f32 v212, v104, v105
	v_add_f32_e32 v108, 1.0, v108
	v_add_f32_e32 v109, 1.0, v109
	v_rcp_f32_e32 v108, v108
	v_rcp_f32_e32 v109, v109
	s_nop 0
	v_pk_mul_f32 v[108:109], v[110:111], v[108:109]
	s_nop 0
	v_pk_mul_f32 v[106:107], v[106:107], v[108:109]
	s_nop 0
	v_cvt_pk_bf16_f32 v213, v106, v107
	v_mul_f32_e32 v104, 0xbfb8aa3b, v100
	v_mul_f32_e32 v105, 0xbfb8aa3b, v101
	v_exp_f32_e32 v104, v104
	v_exp_f32_e32 v105, v105
	v_add_f32_e32 v104, 1.0, v104
	v_add_f32_e32 v105, 1.0, v105
	v_rcp_f32_e32 v104, v104
	v_rcp_f32_e32 v105, v105
	s_nop 0
	v_pk_mul_f32 v[100:101], v[100:101], v[104:105]
	s_nop 0
	v_pk_mul_f32 v[96:97], v[96:97], v[100:101]
	v_mul_f32_e32 v100, 0xbfb8aa3b, v102
	v_mul_f32_e32 v101, 0xbfb8aa3b, v103
	v_exp_f32_e32 v100, v100
	v_exp_f32_e32 v101, v101
	v_cvt_pk_bf16_f32 v214, v96, v97
	v_add_f32_e32 v100, 1.0, v100
	v_add_f32_e32 v101, 1.0, v101
	v_rcp_f32_e32 v100, v100
	v_rcp_f32_e32 v101, v101
	s_nop 0
	v_pk_mul_f32 v[100:101], v[102:103], v[100:101]
	s_nop 0
	v_pk_mul_f32 v[98:99], v[98:99], v[100:101]
	s_nop 0
	v_cvt_pk_bf16_f32 v215, v98, v99
	ds_write_b64 v246, v[212:213] offset:8192
	ds_write_b64 v246, v[214:215] offset:12288
	v_mul_f32_e32 v98, 0xbfb8aa3b, v92
	v_mul_f32_e32 v99, 0xbfb8aa3b, v93
	v_exp_f32_e32 v98, v98
	v_exp_f32_e32 v99, v99
	v_add_u32_e32 v96, 0x80, v158
	v_ashrrev_i32_e32 v96, 1, v96
	v_add_f32_e32 v98, 1.0, v98
	v_add_f32_e32 v99, 1.0, v99
	v_rcp_f32_e32 v98, v98
	v_rcp_f32_e32 v99, v99
	v_ashrrev_i32_e32 v97, 31, v96
	v_pk_mul_f32 v[92:93], v[92:93], v[98:99]
	s_nop 0
	v_pk_mul_f32 v[88:89], v[88:89], v[92:93]
	v_mul_f32_e32 v92, 0xbfb8aa3b, v94
	v_mul_f32_e32 v93, 0xbfb8aa3b, v95
	v_exp_f32_e32 v92, v92
	v_exp_f32_e32 v93, v93
	v_add_f32_e32 v92, 1.0, v92
	v_add_f32_e32 v93, 1.0, v93
	v_rcp_f32_e32 v92, v92
	v_rcp_f32_e32 v93, v93
	s_nop 0
	v_pk_mul_f32 v[92:93], v[94:95], v[92:93]
	s_nop 0
	v_pk_mul_f32 v[90:91], v[90:91], v[92:93]
	v_cvt_pk_bf16_f32 v216, v88, v89
	v_lshlrev_b64 v[88:89], 1, v[96:97]
	v_cvt_pk_bf16_f32 v217, v90, v91
	v_mul_f32_e32 v90, 0xbfb8aa3b, v84
	v_mul_f32_e32 v91, 0xbfb8aa3b, v85
	v_exp_f32_e32 v90, v90
	v_exp_f32_e32 v91, v91
	v_add_f32_e32 v90, 1.0, v90
	v_add_f32_e32 v91, 1.0, v91
	v_rcp_f32_e32 v90, v90
	v_rcp_f32_e32 v91, v91
	s_nop 0
	v_pk_mul_f32 v[84:85], v[84:85], v[90:91]
	s_nop 0
	v_pk_mul_f32 v[80:81], v[80:81], v[84:85]
	v_mul_f32_e32 v84, 0xbfb8aa3b, v86
	v_mul_f32_e32 v85, 0xbfb8aa3b, v87
	v_exp_f32_e32 v84, v84
	v_exp_f32_e32 v85, v85
	v_cvt_pk_bf16_f32 v218, v80, v81
	v_add_f32_e32 v84, 1.0, v84
	v_add_f32_e32 v85, 1.0, v85
	v_rcp_f32_e32 v84, v84
	v_rcp_f32_e32 v85, v85
	s_nop 0
	v_pk_mul_f32 v[84:85], v[86:87], v[84:85]
	s_nop 0
	v_pk_mul_f32 v[82:83], v[82:83], v[84:85]
	s_nop 0
	v_cvt_pk_bf16_f32 v219, v82, v83
	ds_write_b64 v247, v[216:217]
	ds_write_b64 v247, v[218:219] offset:4096
	v_mul_f32_e32 v80, 0xbfb8aa3b, v76
	v_mul_f32_e32 v81, 0xbfb8aa3b, v77
	v_exp_f32_e32 v80, v80
	v_exp_f32_e32 v81, v81
	v_add_f32_e32 v80, 1.0, v80
	v_add_f32_e32 v81, 1.0, v81
	v_rcp_f32_e32 v80, v80
	v_rcp_f32_e32 v81, v81
	s_nop 0
	v_pk_mul_f32 v[76:77], v[76:77], v[80:81]
	s_nop 0
	v_pk_mul_f32 v[72:73], v[72:73], v[76:77]
	v_mul_f32_e32 v76, 0xbfb8aa3b, v78
	v_mul_f32_e32 v77, 0xbfb8aa3b, v79
	v_exp_f32_e32 v76, v76
	v_exp_f32_e32 v77, v77
	v_cvt_pk_bf16_f32 v220, v72, v73
	v_add_f32_e32 v76, 1.0, v76
	v_add_f32_e32 v77, 1.0, v77
	v_rcp_f32_e32 v76, v76
	v_rcp_f32_e32 v77, v77
	s_nop 0
	v_pk_mul_f32 v[76:77], v[78:79], v[76:77]
	s_nop 0
	v_pk_mul_f32 v[74:75], v[74:75], v[76:77]
	s_nop 0
	v_cvt_pk_bf16_f32 v221, v74, v75
	v_mul_f32_e32 v72, 0xbfb8aa3b, v68
	v_mul_f32_e32 v73, 0xbfb8aa3b, v69
	v_exp_f32_e32 v72, v72
	v_exp_f32_e32 v73, v73
	v_add_f32_e32 v72, 1.0, v72
	v_add_f32_e32 v73, 1.0, v73
	v_rcp_f32_e32 v72, v72
	v_rcp_f32_e32 v73, v73
	s_nop 0
	v_pk_mul_f32 v[68:69], v[68:69], v[72:73]
	v_mul_f32_e32 v72, 0xbfb8aa3b, v60
	v_mul_f32_e32 v73, 0xbfb8aa3b, v61
	v_exp_f32_e32 v72, v72
	v_exp_f32_e32 v73, v73
	v_pk_mul_f32 v[64:65], v[64:65], v[68:69]
	v_mul_f32_e32 v68, 0xbfb8aa3b, v70
	v_add_f32_e32 v72, 1.0, v72
	v_add_f32_e32 v73, 1.0, v73
	v_rcp_f32_e32 v72, v72
	v_rcp_f32_e32 v73, v73
	v_mul_f32_e32 v69, 0xbfb8aa3b, v71
	v_exp_f32_e32 v68, v68
	v_exp_f32_e32 v69, v69
	v_pk_mul_f32 v[60:61], v[60:61], v[72:73]
	v_cvt_pk_bf16_f32 v222, v64, v65
	v_pk_mul_f32 v[56:57], v[56:57], v[60:61]
	v_mul_f32_e32 v60, 0xbfb8aa3b, v62
	v_mul_f32_e32 v61, 0xbfb8aa3b, v63
	v_exp_f32_e32 v60, v60
	v_exp_f32_e32 v61, v61
	v_add_f32_e32 v68, 1.0, v68
	v_add_f32_e32 v69, 1.0, v69
	v_rcp_f32_e32 v68, v68
	v_rcp_f32_e32 v69, v69
	v_add_f32_e32 v60, 1.0, v60
	v_add_f32_e32 v61, 1.0, v61
	v_rcp_f32_e32 v60, v60
	v_rcp_f32_e32 v61, v61
	v_pk_mul_f32 v[68:69], v[70:71], v[68:69]
	v_cvt_pk_bf16_f32 v224, v56, v57
	v_pk_mul_f32 v[66:67], v[66:67], v[68:69]
	v_pk_mul_f32 v[60:61], v[62:63], v[60:61]
	v_cvt_pk_bf16_f32 v223, v66, v67
	ds_write_b64 v247, v[220:221] offset:8192
	ds_write_b64 v247, v[222:223] offset:12288
	v_add_u32_e32 v64, 0x80, v153
	v_mad_i64_i32 v[70:71], s[34:35], v64, s13, v[136:137]
	v_pk_mul_f32 v[58:59], v[58:59], v[60:61]
	v_add_u32_e32 v64, 0x90, v153
	v_cvt_pk_bf16_f32 v225, v58, v59
	v_mul_f32_e32 v56, 0xbfb8aa3b, v52
	v_mul_f32_e32 v57, 0xbfb8aa3b, v53
	v_exp_f32_e32 v56, v56
	v_exp_f32_e32 v57, v57
	v_mad_i64_i32 v[68:69], s[34:35], v64, s13, v[136:137]
	v_add_f32_e32 v56, 1.0, v56
	v_add_f32_e32 v57, 1.0, v57
	v_rcp_f32_e32 v56, v56
	v_rcp_f32_e32 v57, v57
	v_add_u32_e32 v64, 0xa0, v153
	v_mad_i64_i32 v[66:67], s[34:35], v64, s13, v[136:137]
	v_pk_mul_f32 v[52:53], v[52:53], v[56:57]
	v_add_u32_e32 v64, 0xb0, v153
	v_pk_mul_f32 v[48:49], v[48:49], v[52:53]
	v_mul_f32_e32 v52, 0xbfb8aa3b, v54
	v_mul_f32_e32 v53, 0xbfb8aa3b, v55
	v_exp_f32_e32 v52, v52
	v_exp_f32_e32 v53, v53
	v_cvt_pk_bf16_f32 v226, v48, v49
	v_mad_i64_i32 v[64:65], s[34:35], v64, s13, v[136:137]
	v_add_f32_e32 v52, 1.0, v52
	v_add_f32_e32 v53, 1.0, v53
	v_rcp_f32_e32 v52, v52
	v_rcp_f32_e32 v53, v53
	s_nop 0
	v_pk_mul_f32 v[52:53], v[54:55], v[52:53]
	s_nop 0
	v_pk_mul_f32 v[50:51], v[50:51], v[52:53]
	s_nop 0
	v_cvt_pk_bf16_f32 v227, v50, v51
	ds_write_b64 v248, v[224:225]
	ds_write_b64 v248, v[226:227] offset:4096
	v_mul_f32_e32 v48, 0xbfb8aa3b, v44
	v_mul_f32_e32 v49, 0xbfb8aa3b, v45
	v_exp_f32_e32 v48, v48
	v_exp_f32_e32 v49, v49
	v_add_f32_e32 v48, 1.0, v48
	v_add_f32_e32 v49, 1.0, v49
	v_rcp_f32_e32 v48, v48
	v_rcp_f32_e32 v49, v49
	s_nop 0
	v_pk_mul_f32 v[44:45], v[44:45], v[48:49]
	s_nop 0
	v_pk_mul_f32 v[40:41], v[40:41], v[44:45]
	v_mul_f32_e32 v44, 0xbfb8aa3b, v46
	v_mul_f32_e32 v45, 0xbfb8aa3b, v47
	v_exp_f32_e32 v44, v44
	v_exp_f32_e32 v45, v45
	v_cvt_pk_bf16_f32 v228, v40, v41
	v_add_f32_e32 v44, 1.0, v44
	v_add_f32_e32 v45, 1.0, v45
	v_rcp_f32_e32 v44, v44
	v_rcp_f32_e32 v45, v45
	s_nop 0
	v_pk_mul_f32 v[44:45], v[46:47], v[44:45]
	s_nop 0
	v_pk_mul_f32 v[42:43], v[42:43], v[44:45]
	s_nop 0
	v_cvt_pk_bf16_f32 v229, v42, v43
	v_mul_f32_e32 v40, 0xbfb8aa3b, v36
	v_mul_f32_e32 v41, 0xbfb8aa3b, v37
	v_exp_f32_e32 v40, v40
	v_exp_f32_e32 v41, v41
	v_add_f32_e32 v40, 1.0, v40
	v_add_f32_e32 v41, 1.0, v41
	v_rcp_f32_e32 v40, v40
	v_rcp_f32_e32 v41, v41
	s_nop 0
	v_pk_mul_f32 v[36:37], v[36:37], v[40:41]
	s_nop 0
	v_pk_mul_f32 v[32:33], v[32:33], v[36:37]
	v_mul_f32_e32 v36, 0xbfb8aa3b, v38
	v_mul_f32_e32 v37, 0xbfb8aa3b, v39
	v_exp_f32_e32 v36, v36
	v_exp_f32_e32 v37, v37
	v_cvt_pk_bf16_f32 v230, v32, v33
	v_add_f32_e32 v36, 1.0, v36
	v_add_f32_e32 v37, 1.0, v37
	v_rcp_f32_e32 v36, v36
	v_rcp_f32_e32 v37, v37
	s_nop 0
	v_pk_mul_f32 v[36:37], v[38:39], v[36:37]
	s_nop 0
	v_pk_mul_f32 v[34:35], v[34:35], v[36:37]
	s_nop 0
	v_cvt_pk_bf16_f32 v231, v34, v35
	ds_write_b64 v248, v[228:229] offset:8192
	ds_write_b64 v248, v[230:231] offset:12288
	v_mul_f32_e32 v32, 0xbfb8aa3b, v28
	v_mul_f32_e32 v33, 0xbfb8aa3b, v29
	v_exp_f32_e32 v32, v32
	v_exp_f32_e32 v33, v33
	v_add_f32_e32 v32, 1.0, v32
	v_add_f32_e32 v33, 1.0, v33
	v_rcp_f32_e32 v32, v32
	v_rcp_f32_e32 v33, v33
	s_nop 0
	v_pk_mul_f32 v[28:29], v[28:29], v[32:33]
	s_nop 0
	v_pk_mul_f32 v[24:25], v[24:25], v[28:29]
	v_mul_f32_e32 v28, 0xbfb8aa3b, v30
	v_mul_f32_e32 v29, 0xbfb8aa3b, v31
	v_exp_f32_e32 v28, v28
	v_exp_f32_e32 v29, v29
	v_cvt_pk_bf16_f32 v232, v24, v25
	v_add_f32_e32 v28, 1.0, v28
	v_add_f32_e32 v29, 1.0, v29
	v_rcp_f32_e32 v28, v28
	v_rcp_f32_e32 v29, v29
	s_nop 0
	v_pk_mul_f32 v[28:29], v[30:31], v[28:29]
	s_nop 0
	v_pk_mul_f32 v[26:27], v[26:27], v[28:29]
	s_nop 0
	v_cvt_pk_bf16_f32 v233, v26, v27
	v_mul_f32_e32 v24, 0xbfb8aa3b, v20
	v_mul_f32_e32 v25, 0xbfb8aa3b, v21
	v_exp_f32_e32 v24, v24
	v_exp_f32_e32 v25, v25
	v_add_f32_e32 v24, 1.0, v24
	v_add_f32_e32 v25, 1.0, v25
	v_rcp_f32_e32 v24, v24
	v_rcp_f32_e32 v25, v25
	s_nop 0
	v_pk_mul_f32 v[20:21], v[20:21], v[24:25]
	s_nop 0
	v_pk_mul_f32 v[16:17], v[16:17], v[20:21]
	v_mul_f32_e32 v20, 0xbfb8aa3b, v22
	v_mul_f32_e32 v21, 0xbfb8aa3b, v23
	v_exp_f32_e32 v20, v20
	v_exp_f32_e32 v21, v21
	v_cvt_pk_bf16_f32 v234, v16, v17
	v_add_f32_e32 v20, 1.0, v20
	v_add_f32_e32 v21, 1.0, v21
	v_rcp_f32_e32 v20, v20
	v_rcp_f32_e32 v21, v21
	s_nop 0
	v_pk_mul_f32 v[20:21], v[22:23], v[20:21]
	s_nop 0
	v_pk_mul_f32 v[18:19], v[18:19], v[20:21]
	s_nop 0
	v_cvt_pk_bf16_f32 v235, v18, v19
	ds_write_b64 v249, v[232:233]
	ds_write_b64 v249, v[234:235] offset:4096
	v_mul_f32_e32 v16, 0xbfb8aa3b, v12
	v_mul_f32_e32 v17, 0xbfb8aa3b, v13
	v_exp_f32_e32 v16, v16
	v_exp_f32_e32 v17, v17
	v_add_f32_e32 v16, 1.0, v16
	v_add_f32_e32 v17, 1.0, v17
	v_rcp_f32_e32 v16, v16
	v_rcp_f32_e32 v17, v17
	s_nop 0
	v_pk_mul_f32 v[12:13], v[12:13], v[16:17]
	s_nop 0
	v_pk_mul_f32 v[8:9], v[8:9], v[12:13]
	v_mul_f32_e32 v12, 0xbfb8aa3b, v14
	v_mul_f32_e32 v13, 0xbfb8aa3b, v15
	v_exp_f32_e32 v12, v12
	v_exp_f32_e32 v13, v13
	v_cvt_pk_bf16_f32 v236, v8, v9
	v_add_f32_e32 v12, 1.0, v12
	v_add_f32_e32 v13, 1.0, v13
	v_rcp_f32_e32 v12, v12
	v_rcp_f32_e32 v13, v13
	s_nop 0
	v_pk_mul_f32 v[12:13], v[14:15], v[12:13]
	s_nop 0
	v_pk_mul_f32 v[10:11], v[10:11], v[12:13]
	s_nop 0
	v_cvt_pk_bf16_f32 v237, v10, v11
	v_mul_f32_e32 v8, 0xbfb8aa3b, v4
	v_mul_f32_e32 v9, 0xbfb8aa3b, v5
	v_exp_f32_e32 v8, v8
	v_exp_f32_e32 v9, v9
	v_add_f32_e32 v8, 1.0, v8
	v_add_f32_e32 v9, 1.0, v9
	v_rcp_f32_e32 v8, v8
	v_rcp_f32_e32 v9, v9
	s_nop 0
	v_pk_mul_f32 v[4:5], v[4:5], v[8:9]
	s_nop 0
	v_pk_mul_f32 v[0:1], v[0:1], v[4:5]
	v_mul_f32_e32 v4, 0xbfb8aa3b, v6
	v_mul_f32_e32 v5, 0xbfb8aa3b, v7
	v_exp_f32_e32 v4, v4
	v_exp_f32_e32 v5, v5
	v_cvt_pk_bf16_f32 v238, v0, v1
	v_add_f32_e32 v4, 1.0, v4
	v_add_f32_e32 v5, 1.0, v5
	v_rcp_f32_e32 v4, v4
	v_rcp_f32_e32 v5, v5
	s_nop 0
	v_pk_mul_f32 v[4:5], v[6:7], v[4:5]
	s_nop 0
	v_pk_mul_f32 v[2:3], v[2:3], v[4:5]
	s_nop 0
	v_cvt_pk_bf16_f32 v239, v2, v3
	ds_write_b64 v249, v[236:237] offset:8192
	ds_write_b64 v249, v[238:239] offset:12288
	s_waitcnt lgkmcnt(0)
	s_barrier
	v_and_b32_e32 v58, 63, v131
	v_lshrrev_b32_e32 v59, 6, v131
	v_and_b32_e32 v60, 15, v58
	v_lshrrev_b32_e32 v61, 4, v58
	v_and_b32_e32 v62, 3, v59
	v_lshl_add_u32 v62, v62, 5, v61
	v_lshlrev_b32_e32 v62, 8, v62
	v_lshrrev_b32_e32 v63, 2, v59
	v_lshl_add_u32 v62, v63, 16, v62
	v_add_u32_e32 v62, 0x8020, v62
	v_xor_b32_e32 v63, v60, v61
	v_lshl_add_u32 v98, v63, 4, v62
	v_xor_b32_e32 v64, 4, v63
	v_lshl_add_u32 v99, v64, 4, v62
	v_xor_b32_e32 v64, 8, v63
	v_lshl_add_u32 v100, v64, 4, v62
	v_xor_b32_e32 v64, 12, v63
	v_lshl_add_u32 v101, v64, 4, v62
	ds_read_b128 v[4:7], v98
	ds_read_b128 v[8:11], v99 offset:1024
	ds_read_b128 v[20:23], v100 offset:2048
	ds_read_b128 v[24:27], v101 offset:3072
	ds_read_b128 v[28:31], v98 offset:4096
	ds_read_b128 v[32:35], v99 offset:5120
	ds_read_b128 v[36:39], v100 offset:6144
	ds_read_b128 v[40:43], v101 offset:7168
	v_mov_b32_e32 v102, 0x1600
	v_mov_b32_e32 v50, s80
	v_mov_b32_e32 v51, s81
	v_mad_i64_i32 v[46:47], s[94:95], v240, v102, v[50:51]
	v_mov_b32_e32 v44, v241
	v_mov_b32_e32 v45, 0
	v_mov_b32_e32 v48, 0x5800
	v_mov_b32_e32 v49, 0
	v_lshl_add_u64 v[46:47], v[46:47], 0, v[44:45]
	s_waitcnt lgkmcnt(7)
	global_store_dwordx4 v[46:47], v[4:7], off
	v_lshl_add_u64 v[46:47], v[46:47], 0, v[48:49]
	s_waitcnt lgkmcnt(6)
	global_store_dwordx4 v[46:47], v[8:11], off
	v_lshl_add_u64 v[46:47], v[46:47], 0, v[48:49]
	s_waitcnt lgkmcnt(5)
	global_store_dwordx4 v[46:47], v[20:23], off
	v_lshl_add_u64 v[46:47], v[46:47], 0, v[48:49]
	s_waitcnt lgkmcnt(4)
	global_store_dwordx4 v[46:47], v[24:27], off
	v_lshl_add_u64 v[46:47], v[46:47], 0, v[48:49]
	s_waitcnt lgkmcnt(3)
	global_store_dwordx4 v[46:47], v[28:31], off
	v_lshl_add_u64 v[46:47], v[46:47], 0, v[48:49]
	s_waitcnt lgkmcnt(2)
	global_store_dwordx4 v[46:47], v[32:35], off
	v_lshl_add_u64 v[46:47], v[46:47], 0, v[48:49]
	s_waitcnt lgkmcnt(1)
	global_store_dwordx4 v[46:47], v[36:39], off
	v_lshl_add_u64 v[46:47], v[46:47], 0, v[48:49]
	s_waitcnt lgkmcnt(0)
	global_store_dwordx4 v[46:47], v[40:43], off
	s_cbranch_vccz .LBB0_1970
